# speedup vs baseline: 1.0142x; 1.0024x over previous
; DI void attn_unit(const Params& P, LAS unsigned char* lds, int b, int h, int qb, bool dry) {
;     ...
;         float mx = fmaxf(fmaxf(s0[0], s0[1]), s0[2]);
; #pragma unroll
;         for (int i = 3; i < 15; i += 2) mx = fmaxf(fmaxf(mx, s0[i]), s0[i + 1]);
;         mx = fmaxf(fmaxf(mx, s0[15]), s1[0]);
; #pragma unroll
;         for (int i = 1; i < 15; i += 2) mx = fmaxf(fmaxf(mx, s1[i]), s1[i + 1]);
;         mx = fmaxf(mx, s1[15]);
;         { const auto rr = __builtin_amdgcn_permlane32_swap(__float_as_uint(mx), __float_as_uint(mx), false, false);
;           mx = fmaxf(__uint_as_float(rr[0]), __uint_as_float(rr[1])); }
;         if (__builtin_amdgcn_ballot_w64(mx > mrun + 8.f)) {
.LBB0_38:
	s_nop 6
	v_max_f32_e32 v221, v80, v81
	v_max3_f32 v221, v221, v82, v83
	v_max3_f32 v221, v221, v84, v85
	v_max3_f32 v221, v221, v86, v87
	v_max3_f32 v221, v221, v88, v89
	v_max3_f32 v221, v221, v90, v91
	v_max3_f32 v221, v221, v92, v93
	v_max3_f32 v221, v221, v94, v95
	v_max3_f32 v221, v221, v64, v65
	v_max3_f32 v221, v221, v66, v67
	v_max3_f32 v221, v221, v68, v69
	v_max3_f32 v221, v221, v70, v71
	v_max3_f32 v221, v221, v72, v73
	v_max3_f32 v221, v221, v74, v75
	v_max3_f32 v221, v221, v76, v77
	v_max3_f32 v221, v221, v78, v79
	v_mov_b32_e32 v222, v221
	s_nop 1
	v_permlane32_swap_b32_e32 v221, v222
	v_max_f32_e32 v221, v221, v222
	v_cmp_lt_f32_e32 vcc, 0x41000000, v221
	s_cmp_eq_u32 s20, 2
	s_cbranch_scc1 .Lfold_r0
	s_cbranch_vccz .LBB0_40

; #define LAS __attribute__((address_space(3)))
; DI unsigned pk_bf16(float lo, float hi) { unsigned r; asm("v_cvt_pk_bf16_f32 %0, %1, %2" : "=v"(r) : "v"(lo), "v"(hi)); return r; }
; #define MFMA32(a, b, c) __builtin_amdgcn_mfma_f32_32x32x16_bf16((a), (b), (c), 0, 0, 0)
; DI bf16x8 cat4(s16x4 lo, s16x4 hi) { return __builtin_shufflevector(lo, hi, 0, 1, 2, 3, 4, 5, 6, 7); }
; DI void attn_unit(const Params& P, LAS unsigned char* lds, int b, int h, int qb, bool dry) {
;     ...
;         f32x2_ ls2 = {0.f, 0.f};
;         const f32x2_ m2 = {mrun, mrun};
; #pragma unroll
;         for (int i = 0; i < 16; i += 2) {
;             f32x2_ t = (f32x2_){s0[i], s0[i + 1]} - m2; t.x = __builtin_amdgcn_exp2f(t.x); t.y = __builtin_amdgcn_exp2f(t.y); ls2 += t; s0[i] = t.x; s0[i + 1] = t.y;
;             f32x2_ u = (f32x2_){s1[i], s1[i + 1]} - m2; u.x = __builtin_amdgcn_exp2f(u.x); u.y = __builtin_amdgcn_exp2f(u.y); ls2 += u; s1[i] = u.x; s1[i + 1] = u.y;
;         }
;         lrun += ls2.x + ls2.y;
; #pragma unroll
;         for (int s2 = 0; s2 < 2; ++s2) {
;             u32x4 t0, t1;
;             t0.x = pk_bf16(s0[8 * s2 + 0], s0[8 * s2 + 1]); t0.y = pk_bf16(s0[8 * s2 + 2], s0[8 * s2 + 3]); t0.z = pk_bf16(s0[8 * s2 + 4], s0[8 * s2 + 5]); t0.w = pk_bf16(s0[8 * s2 + 6], s0[8 * s2 + 7]);
;             t1.x = pk_bf16(s1[8 * s2 + 0], s1[8 * s2 + 1]); t1.y = pk_bf16(s1[8 * s2 + 2], s1[8 * s2 + 3]); t1.z = pk_bf16(s1[8 * s2 + 4], s1[8 * s2 + 5]); t1.w = pk_bf16(s1[8 * s2 + 6], s1[8 * s2 + 7]);
;             pf[0][s2] = __builtin_bit_cast(bf16x8, t0); pf[1][s2] = __builtin_bit_cast(bf16x8, t1);
;         }
;     };
;     auto pv = [&](int vslot) {
;         const LAS unsigned char* vb_ = Vs + vslot * VS_BYTES + r * VS_STRIDE + 8 * hh;
; #pragma unroll
;         for (int kb = 0; kb < 2; ++kb)
; #pragma unroll
;             for (int s2 = 0; s2 < 2; ++s2)
; #pragma unroll
;                 for (int d = 0; d < 4; ++d) {
;                     const LAS unsigned char* p = vb_ + d * 32 * VS_STRIDE + (32 * kb + 16 * s2) * 2;
;                     const bf16x8 a = cat4(*(const LAS s16x4*)p, *(const LAS s16x4*)(p + 16));
;                     o[d] = MFMA32(a, pf[kb][s2], o[d]);
;                 }
.LBB0_40:
	v_add_u32_e32 v221, 0xc800, v216
	ds_read2_b64 v[222:225], v221 offset1:2
	v_add_u32_e32 v240, 0xf800, v216
	v_exp_f32_e32 v230, v86
	v_exp_f32_e32 v231, v87
	v_exp_f32_e32 v232, v88
	v_exp_f32_e32 v233, v89
	ds_read2_b64 v[86:89], v240 offset0:96 offset1:98
	v_exp_f32_e32 v234, v90
	v_exp_f32_e32 v235, v91
	v_add_u32_e32 v238, 0xd800, v216
	v_exp_f32_e32 v236, v92
	v_exp_f32_e32 v237, v93
	ds_read2_b64 v[90:93], v221 offset0:4 offset1:6
	v_exp_f32_e32 v80, v80
	v_exp_f32_e32 v81, v81
	v_exp_f32_e32 v82, v82
	v_exp_f32_e32 v83, v83
	v_exp_f32_e32 v84, v84
	v_exp_f32_e32 v85, v85
	v_cvt_pk_bf16_f32 v226, v80, v81
	v_cvt_pk_bf16_f32 v227, v82, v83
	v_cvt_pk_bf16_f32 v228, v84, v85
	v_cvt_pk_bf16_f32 v229, v230, v231
	v_add_u32_e32 v239, 0xe800, v216
	s_waitcnt lgkmcnt(0)
	v_mfma_f32_32x32x16_bf16 v[48:63], v[222:225], v[226:229], v[48:63]
	ds_read2_b64 v[222:225], v238 offset0:32 offset1:34
	v_mfma_f32_32x32x16_bf16 v[0:15], v[86:89], v[226:229], v[0:15]
	v_cvt_pk_bf16_f32 v88, v236, v237
	v_exp_f32_e32 v94, v94
	v_exp_f32_e32 v95, v95
	v_cvt_pk_bf16_f32 v86, v232, v233
	v_cvt_pk_bf16_f32 v87, v234, v235
	v_cvt_pk_bf16_f32 v89, v94, v95
	s_waitcnt lgkmcnt(0)
	v_mfma_f32_32x32x16_bf16 v[32:47], v[222:225], v[226:229], v[32:47]
	ds_read2_b64 v[222:225], v239 offset0:64 offset1:66
	v_mfma_f32_32x32x16_bf16 v[48:63], v[90:93], v[86:89], v[48:63]
	ds_read2_b64 v[90:93], v238 offset0:36 offset1:38
	s_waitcnt lgkmcnt(0)
	v_mfma_f32_32x32x16_bf16 v[32:47], v[90:93], v[86:89], v[32:47]
	ds_read2_b64 v[90:93], v239 offset0:68 offset1:70
	v_mfma_f32_32x32x16_bf16 v[16:31], v[222:225], v[226:229], v[16:31]
	v_exp_f32_e32 v226, v64
	v_exp_f32_e32 v227, v65
	ds_read2_b64 v[222:225], v240 offset0:100 offset1:102
	s_waitcnt lgkmcnt(0)
	v_mfma_f32_32x32x16_bf16 v[16:31], v[90:93], v[86:89], v[16:31]
	v_exp_f32_e32 v90, v66
	v_exp_f32_e32 v91, v67
	v_exp_f32_e32 v92, v68
	v_exp_f32_e32 v93, v69
	ds_read2_b64 v[64:67], v221 offset0:8 offset1:10
	v_mfma_f32_32x32x16_bf16 v[0:15], v[222:225], v[86:89], v[0:15]
	v_exp_f32_e32 v222, v70
	v_exp_f32_e32 v223, v71
	v_cvt_pk_bf16_f32 v68, v226, v227
	v_cvt_pk_bf16_f32 v69, v90, v91
	v_cvt_pk_bf16_f32 v70, v92, v93
	v_cvt_pk_bf16_f32 v71, v222, v223
	ds_read2_b64 v[86:89], v240 offset0:104 offset1:106
	s_waitcnt lgkmcnt(0)
	v_mfma_f32_32x32x16_bf16 v[48:63], v[64:67], v[68:71], v[48:63]
	ds_read2_b64 v[64:67], v238 offset0:40 offset1:42
	v_exp_f32_e32 v224, v72
	v_exp_f32_e32 v225, v73
	v_pk_add_f32 v[72:73], v[80:81], 0 op_sel_hi:[1,0]
	s_nop 0
	v_add_f32_e64 v72, v226, v72
	v_add_f32_e64 v73, v227, v73
	s_waitcnt lgkmcnt(0)
	v_mfma_f32_32x32x16_bf16 v[32:47], v[64:67], v[68:71], v[32:47]
	ds_read2_b64 v[64:67], v239 offset0:72 offset1:74
	v_add_f32_e64 v72, v82, v72
	v_add_f32_e64 v73, v83, v73
	v_add_f32_e64 v72, v90, v72
	v_add_f32_e64 v73, v91, v73
	v_add_f32_e64 v80, v84, v72
	v_add_f32_e64 v81, v85, v73
	s_waitcnt lgkmcnt(0)
	v_mfma_f32_32x32x16_bf16 v[16:31], v[64:67], v[68:71], v[16:31]
	v_mov_b32_e32 v64, v74
	v_mov_b32_e32 v65, v75
	ds_read2_b64 v[72:75], v239 offset0:76 offset1:78
	v_exp_f32_e32 v228, v64
	v_exp_f32_e32 v229, v65
	s_nop 0
	v_exp_f32_e32 v76, v76
	v_exp_f32_e32 v77, v77
	ds_read2_b64 v[64:67], v221 offset0:12 offset1:14
	v_mfma_f32_32x32x16_bf16 v[0:15], v[86:89], v[68:71], v[0:15]
	v_cvt_pk_bf16_f32 v70, v76, v77
	v_exp_f32_e32 v78, v78
	v_exp_f32_e32 v79, v79
	v_cvt_pk_bf16_f32 v68, v224, v225
	v_cvt_pk_bf16_f32 v69, v228, v229
	v_cvt_pk_bf16_f32 v71, v78, v79
	s_waitcnt lgkmcnt(0)
	s_nop 0
	v_mfma_f32_32x32x16_bf16 v[48:63], v[64:67], v[68:71], v[48:63]
	ds_read2_b64 v[64:67], v238 offset0:44 offset1:46
	s_waitcnt lgkmcnt(0)
	v_mfma_f32_32x32x16_bf16 v[32:47], v[64:67], v[68:71], v[32:47]
	v_add_f32_e64 v64, v92, v80
	v_add_f32_e64 v65, v93, v81
	v_add_f32_e64 v64, v230, v64
	v_add_f32_e64 v65, v231, v65
	v_add_f32_e64 v64, v222, v64
	v_add_f32_e64 v65, v223, v65
	v_add_f32_e64 v64, v232, v64
	v_add_f32_e64 v65, v233, v65
	v_mfma_f32_32x32x16_bf16 v[16:31], v[72:75], v[68:71], v[16:31]
	v_add_f32_e64 v64, v224, v64
	v_add_f32_e64 v65, v225, v65
	v_add_f32_e64 v80, v234, v64
	v_add_f32_e64 v81, v235, v65
	ds_read2_b64 v[64:67], v240 offset0:108 offset1:110
	v_add_f32_e64 v72, v228, v80
	v_add_f32_e64 v73, v229, v81
	s_nop 0
	v_add_f32_e64 v72, v236, v72
	v_add_f32_e64 v73, v237, v73
	s_waitcnt lgkmcnt(0)
	v_mfma_f32_32x32x16_bf16 v[0:15], v[64:67], v[68:71], v[0:15]
	v_add_f32_e64 v72, v76, v72
	v_add_f32_e64 v73, v77, v73
	v_add_f32_e64 v72, v94, v72
	v_add_f32_e64 v73, v95, v73
	v_add_f32_e64 v72, v78, v72
	v_add_f32_e64 v73, v79, v73
	v_add_f32_e32 v72, v72, v73
	v_add_f32_e32 v215, v215, v72
	s_branch .Lattn_wdone0

; DI void attn_unit(const Params& P, LAS unsigned char* lds, int b, int h, int qb, bool dry) {
;     ...
;         float mx = fmaxf(fmaxf(s0[0], s0[1]), s0[2]);
; #pragma unroll
;         for (int i = 3; i < 15; i += 2) mx = fmaxf(fmaxf(mx, s0[i]), s0[i + 1]);
;         mx = fmaxf(fmaxf(mx, s0[15]), s1[0]);
; #pragma unroll
;         for (int i = 1; i < 15; i += 2) mx = fmaxf(fmaxf(mx, s1[i]), s1[i + 1]);
;         mx = fmaxf(mx, s1[15]);
;         { const auto rr = __builtin_amdgcn_permlane32_swap(__float_as_uint(mx), __float_as_uint(mx), false, false);
;           mx = fmaxf(__uint_as_float(rr[0]), __uint_as_float(rr[1])); }
;         if (__builtin_amdgcn_ballot_w64(mx > mrun + 8.f)) {
.LBB0_47:
	s_nop 6
	v_max_f32_e32 v220, v80, v81
	v_max3_f32 v220, v220, v82, v83
	v_max3_f32 v220, v220, v84, v85
	v_max3_f32 v220, v220, v86, v87
	v_max3_f32 v220, v220, v88, v89
	v_max3_f32 v220, v220, v90, v91
	v_max3_f32 v220, v220, v92, v93
	v_max3_f32 v220, v220, v94, v95
	v_max3_f32 v220, v220, v64, v65
	v_max3_f32 v220, v220, v66, v67
	v_max3_f32 v220, v220, v68, v69
	v_max3_f32 v220, v220, v70, v71
	v_max3_f32 v220, v220, v72, v73
	v_max3_f32 v220, v220, v74, v75
	v_max3_f32 v220, v220, v76, v77
	v_max3_f32 v220, v220, v78, v79
	v_mov_b32_e32 v221, v220
	s_nop 1
	v_permlane32_swap_b32_e32 v220, v221
	v_max_f32_e32 v220, v220, v221
	v_cmp_lt_f32_e32 vcc, 0x41000000, v220
	s_cbranch_vccz .LBB0_49

; #define LAS __attribute__((address_space(3)))
; DI unsigned pk_bf16(float lo, float hi) { unsigned r; asm("v_cvt_pk_bf16_f32 %0, %1, %2" : "=v"(r) : "v"(lo), "v"(hi)); return r; }
; #define MFMA32(a, b, c) __builtin_amdgcn_mfma_f32_32x32x16_bf16((a), (b), (c), 0, 0, 0)
; DI bf16x8 cat4(s16x4 lo, s16x4 hi) { return __builtin_shufflevector(lo, hi, 0, 1, 2, 3, 4, 5, 6, 7); }
; DI void attn_unit(const Params& P, LAS unsigned char* lds, int b, int h, int qb, bool dry) {
;     ...
;         f32x2_ ls2 = {0.f, 0.f};
;         const f32x2_ m2 = {mrun, mrun};
; #pragma unroll
;         for (int i = 0; i < 16; i += 2) {
;             f32x2_ t = (f32x2_){s0[i], s0[i + 1]} - m2; t.x = __builtin_amdgcn_exp2f(t.x); t.y = __builtin_amdgcn_exp2f(t.y); ls2 += t; s0[i] = t.x; s0[i + 1] = t.y;
;             f32x2_ u = (f32x2_){s1[i], s1[i + 1]} - m2; u.x = __builtin_amdgcn_exp2f(u.x); u.y = __builtin_amdgcn_exp2f(u.y); ls2 += u; s1[i] = u.x; s1[i + 1] = u.y;
;         }
;         lrun += ls2.x + ls2.y;
; #pragma unroll
;         for (int s2 = 0; s2 < 2; ++s2) {
;             u32x4 t0, t1;
;             t0.x = pk_bf16(s0[8 * s2 + 0], s0[8 * s2 + 1]); t0.y = pk_bf16(s0[8 * s2 + 2], s0[8 * s2 + 3]); t0.z = pk_bf16(s0[8 * s2 + 4], s0[8 * s2 + 5]); t0.w = pk_bf16(s0[8 * s2 + 6], s0[8 * s2 + 7]);
;             t1.x = pk_bf16(s1[8 * s2 + 0], s1[8 * s2 + 1]); t1.y = pk_bf16(s1[8 * s2 + 2], s1[8 * s2 + 3]); t1.z = pk_bf16(s1[8 * s2 + 4], s1[8 * s2 + 5]); t1.w = pk_bf16(s1[8 * s2 + 6], s1[8 * s2 + 7]);
;             pf[0][s2] = __builtin_bit_cast(bf16x8, t0); pf[1][s2] = __builtin_bit_cast(bf16x8, t1);
;         }
;     };
;     auto pv = [&](int vslot) {
;         const LAS unsigned char* vb_ = Vs + vslot * VS_BYTES + r * VS_STRIDE + 8 * hh;
; #pragma unroll
;         for (int kb = 0; kb < 2; ++kb)
; #pragma unroll
;             for (int s2 = 0; s2 < 2; ++s2)
; #pragma unroll
;                 for (int d = 0; d < 4; ++d) {
;                     const LAS unsigned char* p = vb_ + d * 32 * VS_STRIDE + (32 * kb + 16 * s2) * 2;
;                     const bf16x8 a = cat4(*(const LAS s16x4*)p, *(const LAS s16x4*)(p + 16));
;                     o[d] = MFMA32(a, pf[kb][s2], o[d]);
;                 }
.LBB0_49:
	ds_read2_b64 v[220:223], v218 offset1:2
	v_add_u32_e32 v238, 0x3000, v218
	v_exp_f32_e32 v228, v86
	v_exp_f32_e32 v229, v87
	v_exp_f32_e32 v230, v88
	v_exp_f32_e32 v231, v89
	ds_read2_b64 v[86:89], v238 offset0:96 offset1:98
	v_exp_f32_e32 v232, v90
	v_exp_f32_e32 v233, v91
	v_add_u32_e32 v236, 0x1000, v218
	v_exp_f32_e32 v234, v92
	v_exp_f32_e32 v235, v93
	ds_read2_b64 v[90:93], v218 offset0:4 offset1:6
	v_exp_f32_e32 v80, v80
	v_exp_f32_e32 v81, v81
	v_exp_f32_e32 v82, v82
	v_exp_f32_e32 v83, v83
	v_exp_f32_e32 v84, v84
	v_exp_f32_e32 v85, v85
	v_cvt_pk_bf16_f32 v224, v80, v81
	v_cvt_pk_bf16_f32 v225, v82, v83
	v_cvt_pk_bf16_f32 v226, v84, v85
	v_cvt_pk_bf16_f32 v227, v228, v229
	v_add_u32_e32 v237, 0x2000, v218
	s_waitcnt lgkmcnt(0)
	v_mfma_f32_32x32x16_bf16 v[48:63], v[220:223], v[224:227], v[48:63]
	ds_read2_b64 v[220:223], v236 offset0:32 offset1:34
	v_mfma_f32_32x32x16_bf16 v[0:15], v[86:89], v[224:227], v[0:15]
	v_cvt_pk_bf16_f32 v88, v234, v235
	v_exp_f32_e32 v94, v94
	v_exp_f32_e32 v95, v95
	v_cvt_pk_bf16_f32 v86, v230, v231
	v_cvt_pk_bf16_f32 v87, v232, v233
	v_cvt_pk_bf16_f32 v89, v94, v95
	s_waitcnt lgkmcnt(0)
	v_mfma_f32_32x32x16_bf16 v[32:47], v[220:223], v[224:227], v[32:47]
	ds_read2_b64 v[220:223], v237 offset0:64 offset1:66
	v_mfma_f32_32x32x16_bf16 v[48:63], v[90:93], v[86:89], v[48:63]
	ds_read2_b64 v[90:93], v236 offset0:36 offset1:38
	s_waitcnt lgkmcnt(0)
	v_mfma_f32_32x32x16_bf16 v[32:47], v[90:93], v[86:89], v[32:47]
	ds_read2_b64 v[90:93], v237 offset0:68 offset1:70
	v_mfma_f32_32x32x16_bf16 v[16:31], v[220:223], v[224:227], v[16:31]
	v_exp_f32_e32 v224, v64
	v_exp_f32_e32 v225, v65
	ds_read2_b64 v[220:223], v238 offset0:100 offset1:102
	s_waitcnt lgkmcnt(0)
	v_mfma_f32_32x32x16_bf16 v[16:31], v[90:93], v[86:89], v[16:31]
	v_exp_f32_e32 v90, v66
	v_exp_f32_e32 v91, v67
	v_exp_f32_e32 v92, v68
	v_exp_f32_e32 v93, v69
	ds_read2_b64 v[64:67], v218 offset0:8 offset1:10
	v_mfma_f32_32x32x16_bf16 v[0:15], v[220:223], v[86:89], v[0:15]
	v_exp_f32_e32 v220, v70
	v_exp_f32_e32 v221, v71
	v_cvt_pk_bf16_f32 v68, v224, v225
	v_cvt_pk_bf16_f32 v69, v90, v91
	v_cvt_pk_bf16_f32 v70, v92, v93
	v_cvt_pk_bf16_f32 v71, v220, v221
	ds_read2_b64 v[86:89], v238 offset0:104 offset1:106
	s_waitcnt lgkmcnt(0)
	v_mfma_f32_32x32x16_bf16 v[48:63], v[64:67], v[68:71], v[48:63]
	ds_read2_b64 v[64:67], v236 offset0:40 offset1:42
	v_exp_f32_e32 v222, v72
	v_exp_f32_e32 v223, v73
	v_pk_add_f32 v[72:73], v[80:81], 0 op_sel_hi:[1,0]
	s_nop 0
	v_add_f32_e64 v72, v224, v72
	v_add_f32_e64 v73, v225, v73
	s_waitcnt lgkmcnt(0)
	v_mfma_f32_32x32x16_bf16 v[32:47], v[64:67], v[68:71], v[32:47]
	ds_read2_b64 v[64:67], v237 offset0:72 offset1:74
	v_add_f32_e64 v72, v82, v72
	v_add_f32_e64 v73, v83, v73
	v_add_f32_e64 v72, v90, v72
	v_add_f32_e64 v73, v91, v73
	v_add_f32_e64 v80, v84, v72
	v_add_f32_e64 v81, v85, v73
	s_waitcnt lgkmcnt(0)
	v_mfma_f32_32x32x16_bf16 v[16:31], v[64:67], v[68:71], v[16:31]
	v_mov_b32_e32 v64, v74
	v_mov_b32_e32 v65, v75
	ds_read2_b64 v[72:75], v237 offset0:76 offset1:78
	v_exp_f32_e32 v226, v64
	v_exp_f32_e32 v227, v65
	s_nop 0
	v_exp_f32_e32 v76, v76
	v_exp_f32_e32 v77, v77
	ds_read2_b64 v[64:67], v218 offset0:12 offset1:14
	v_mfma_f32_32x32x16_bf16 v[0:15], v[86:89], v[68:71], v[0:15]
	v_cvt_pk_bf16_f32 v70, v76, v77
	v_exp_f32_e32 v78, v78
	v_exp_f32_e32 v79, v79
	v_cvt_pk_bf16_f32 v68, v222, v223
	v_cvt_pk_bf16_f32 v69, v226, v227
	v_cvt_pk_bf16_f32 v71, v78, v79
	s_waitcnt lgkmcnt(0)
	s_nop 0
	v_mfma_f32_32x32x16_bf16 v[48:63], v[64:67], v[68:71], v[48:63]
	ds_read2_b64 v[64:67], v236 offset0:44 offset1:46
	s_waitcnt lgkmcnt(0)
	v_mfma_f32_32x32x16_bf16 v[32:47], v[64:67], v[68:71], v[32:47]
	v_add_f32_e64 v64, v92, v80
	v_add_f32_e64 v65, v93, v81
	v_add_f32_e64 v64, v228, v64
	v_add_f32_e64 v65, v229, v65
	v_add_f32_e64 v64, v220, v64
	v_add_f32_e64 v65, v221, v65
	v_add_f32_e64 v64, v230, v64
	v_add_f32_e64 v65, v231, v65
	v_mfma_f32_32x32x16_bf16 v[16:31], v[72:75], v[68:71], v[16:31]
	v_add_f32_e64 v64, v222, v64
	v_add_f32_e64 v65, v223, v65
	v_add_f32_e64 v80, v232, v64
	v_add_f32_e64 v81, v233, v65
	ds_read2_b64 v[64:67], v238 offset0:108 offset1:110
	v_add_f32_e64 v72, v226, v80
	v_add_f32_e64 v73, v227, v81
	s_nop 0
	v_add_f32_e64 v72, v234, v72
	v_add_f32_e64 v73, v235, v73
	s_waitcnt lgkmcnt(0)
	v_mfma_f32_32x32x16_bf16 v[0:15], v[64:67], v[68:71], v[0:15]
	v_add_f32_e64 v72, v76, v72
	v_add_f32_e64 v73, v77, v73
	v_add_f32_e64 v72, v94, v72
	v_add_f32_e64 v73, v95, v73
	v_add_f32_e64 v72, v78, v72
	v_add_f32_e64 v73, v79, v73
	v_add_f32_e32 v72, v72, v73
	v_add_f32_e32 v215, v215, v72
	s_branch .LBB0_32
